# PRO_B: the 32 split-K partials of mod loaded up front and added in order with counted waits (was 4 drained groups of 8); on top of v59
# baseline (speedup 1.0000x reference)
; __device__ __forceinline__ void pro_b(const float* const* in, unsigned char* wsl, int cid, int G, int tid) {
;     ...
;     for (int i = cid * NTHR_C + tid; i < L * NB * 6 * D; i += G * NTHR_C) {
;         const int l = i / (NB * 6 * D), n = i % (6 * D); float a = in[3][l * 6 * D + n];
; #pragma unroll 8
;         for (int kc = 0; kc < MOD_KC; ++kc) a += mp[(size_t)kc * (L * NB * 6 * D) + i];
;         MOD[i] = a; }
.LBB0_88:
	v_mul_hi_i32 v1, v0, s2
	v_ashrrev_i32_e32 v5, 13, v1
	v_lshrrev_b32_e32 v6, 31, v1
	v_ashrrev_i32_e32 v1, 11, v1
	v_add_u32_e32 v1, v1, v6
	v_mul_i32_i24_e32 v1, 0x3000, v1
	v_add_u32_e32 v5, v5, v6
	v_sub_u32_e32 v1, v0, v1
	v_mad_i32_i24 v6, v5, s3, v1
	v_ashrrev_i32_e32 v7, 31, v6
	v_lshl_add_u64 v[6:7], v[6:7], 2, s[46:47]
	global_load_dword v5, v[6:7], off
	v_add_co_u32_e32 v8, vcc, 0x31204000, v2
	s_nop 0
	v_addc_co_u32_e32 v9, vcc, 0, v3, vcc
	global_load_dword v130, v[8:9], off
	v_add_co_u32_e32 v8, vcc, 0x312c4000, v2
	s_nop 0
	v_addc_co_u32_e32 v9, vcc, 0, v3, vcc
	global_load_dword v131, v[8:9], off
	v_add_co_u32_e32 v8, vcc, 0x31384000, v2
	s_nop 0
	v_addc_co_u32_e32 v9, vcc, 0, v3, vcc
	global_load_dword v132, v[8:9], off
	v_add_co_u32_e32 v8, vcc, 0x31444000, v2
	s_nop 0
	v_addc_co_u32_e32 v9, vcc, 0, v3, vcc
	global_load_dword v133, v[8:9], off
	v_add_co_u32_e32 v8, vcc, 0x31504000, v2
	s_nop 0
	v_addc_co_u32_e32 v9, vcc, 0, v3, vcc
	global_load_dword v134, v[8:9], off
	v_add_co_u32_e32 v8, vcc, 0x315c4000, v2
	s_nop 0
	v_addc_co_u32_e32 v9, vcc, 0, v3, vcc
	global_load_dword v135, v[8:9], off
	v_add_co_u32_e32 v8, vcc, 0x31684000, v2
	s_nop 0
	v_addc_co_u32_e32 v9, vcc, 0, v3, vcc
	global_load_dword v136, v[8:9], off
	v_add_co_u32_e32 v8, vcc, 0x31744000, v2
	s_nop 0
	v_addc_co_u32_e32 v9, vcc, 0, v3, vcc
	global_load_dword v137, v[8:9], off
	v_add_co_u32_e32 v8, vcc, 0x31804000, v2
	s_nop 0
	v_addc_co_u32_e32 v9, vcc, 0, v3, vcc
	global_load_dword v138, v[8:9], off
	v_add_co_u32_e32 v8, vcc, 0x318c4000, v2
	s_nop 0
	v_addc_co_u32_e32 v9, vcc, 0, v3, vcc
	global_load_dword v139, v[8:9], off
	v_add_co_u32_e32 v8, vcc, 0x31984000, v2
	s_nop 0
	v_addc_co_u32_e32 v9, vcc, 0, v3, vcc
	global_load_dword v140, v[8:9], off
	v_add_co_u32_e32 v8, vcc, 0x31a44000, v2
	s_nop 0
	v_addc_co_u32_e32 v9, vcc, 0, v3, vcc
	global_load_dword v141, v[8:9], off
	v_add_co_u32_e32 v8, vcc, 0x31b04000, v2
	s_nop 0
	v_addc_co_u32_e32 v9, vcc, 0, v3, vcc
	global_load_dword v142, v[8:9], off
	v_add_co_u32_e32 v8, vcc, 0x31bc4000, v2
	s_nop 0
	v_addc_co_u32_e32 v9, vcc, 0, v3, vcc
	global_load_dword v143, v[8:9], off
	v_add_co_u32_e32 v8, vcc, 0x31c84000, v2
	s_nop 0
	v_addc_co_u32_e32 v9, vcc, 0, v3, vcc
	global_load_dword v144, v[8:9], off
	v_add_co_u32_e32 v8, vcc, 0x31d44000, v2
	s_nop 0
	v_addc_co_u32_e32 v9, vcc, 0, v3, vcc
	global_load_dword v145, v[8:9], off
	v_add_co_u32_e32 v8, vcc, 0x31e04000, v2
	s_nop 0
	v_addc_co_u32_e32 v9, vcc, 0, v3, vcc
	global_load_dword v146, v[8:9], off
	v_add_co_u32_e32 v8, vcc, 0x31ec4000, v2
	s_nop 0
	v_addc_co_u32_e32 v9, vcc, 0, v3, vcc
	global_load_dword v147, v[8:9], off
	v_add_co_u32_e32 v8, vcc, 0x31f84000, v2
	s_nop 0
	v_addc_co_u32_e32 v9, vcc, 0, v3, vcc
	global_load_dword v148, v[8:9], off
	v_add_co_u32_e32 v8, vcc, 0x32044000, v2
	s_nop 0
	v_addc_co_u32_e32 v9, vcc, 0, v3, vcc
	global_load_dword v149, v[8:9], off
	v_add_co_u32_e32 v8, vcc, 0x32104000, v2
	s_nop 0
	v_addc_co_u32_e32 v9, vcc, 0, v3, vcc
	global_load_dword v150, v[8:9], off
	v_add_co_u32_e32 v8, vcc, 0x321c4000, v2
	s_nop 0
	v_addc_co_u32_e32 v9, vcc, 0, v3, vcc
	global_load_dword v151, v[8:9], off
	v_add_co_u32_e32 v8, vcc, 0x32284000, v2
	s_nop 0
	v_addc_co_u32_e32 v9, vcc, 0, v3, vcc
	global_load_dword v152, v[8:9], off
	v_add_co_u32_e32 v8, vcc, 0x32344000, v2
	s_nop 0
	v_addc_co_u32_e32 v9, vcc, 0, v3, vcc
	global_load_dword v153, v[8:9], off
	v_add_co_u32_e32 v8, vcc, 0x32404000, v2
	s_nop 0
	v_addc_co_u32_e32 v9, vcc, 0, v3, vcc
	global_load_dword v154, v[8:9], off
	v_add_co_u32_e32 v8, vcc, 0x324c4000, v2
	s_nop 0
	v_addc_co_u32_e32 v9, vcc, 0, v3, vcc
	global_load_dword v155, v[8:9], off
	v_add_co_u32_e32 v8, vcc, 0x32584000, v2
	s_nop 0
	v_addc_co_u32_e32 v9, vcc, 0, v3, vcc
	global_load_dword v156, v[8:9], off
	v_add_co_u32_e32 v8, vcc, 0x32644000, v2
	s_nop 0
	v_addc_co_u32_e32 v9, vcc, 0, v3, vcc
	global_load_dword v157, v[8:9], off
	v_add_co_u32_e32 v8, vcc, 0x32704000, v2
	s_nop 0
	v_addc_co_u32_e32 v9, vcc, 0, v3, vcc
	global_load_dword v158, v[8:9], off
	v_add_co_u32_e32 v8, vcc, 0x327c4000, v2
	s_nop 0
	v_addc_co_u32_e32 v9, vcc, 0, v3, vcc
	global_load_dword v159, v[8:9], off
	v_add_co_u32_e32 v8, vcc, 0x32884000, v2
	s_nop 0
	v_addc_co_u32_e32 v9, vcc, 0, v3, vcc
	global_load_dword v160, v[8:9], off
	v_add_co_u32_e32 v8, vcc, 0x32944000, v2
	s_nop 0
	v_addc_co_u32_e32 v9, vcc, 0, v3, vcc
	global_load_dword v161, v[8:9], off
	s_waitcnt vmcnt(31)
	v_add_f32_e32 v1, v5, v130
	s_waitcnt vmcnt(30)
	v_add_f32_e32 v1, v1, v131
	s_waitcnt vmcnt(29)
	v_add_f32_e32 v1, v1, v132
	s_waitcnt vmcnt(28)
	v_add_f32_e32 v1, v1, v133
	s_waitcnt vmcnt(27)
	v_add_f32_e32 v1, v1, v134
	s_waitcnt vmcnt(26)
	v_add_f32_e32 v1, v1, v135
	s_waitcnt vmcnt(25)
	v_add_f32_e32 v1, v1, v136
	s_waitcnt vmcnt(24)
	v_add_f32_e32 v1, v1, v137
	s_waitcnt vmcnt(23)
	v_add_f32_e32 v1, v1, v138
	s_waitcnt vmcnt(22)
	v_add_f32_e32 v1, v1, v139
	s_waitcnt vmcnt(21)
	v_add_f32_e32 v1, v1, v140
	s_waitcnt vmcnt(20)
	v_add_f32_e32 v1, v1, v141
	s_waitcnt vmcnt(19)
	v_add_f32_e32 v1, v1, v142
	s_waitcnt vmcnt(18)
	v_add_f32_e32 v1, v1, v143
	s_waitcnt vmcnt(17)
	v_add_f32_e32 v1, v1, v144
	s_waitcnt vmcnt(16)
	v_add_f32_e32 v1, v1, v145
	s_waitcnt vmcnt(15)
	v_add_f32_e32 v1, v1, v146
	s_waitcnt vmcnt(14)
	v_add_f32_e32 v1, v1, v147
	s_waitcnt vmcnt(13)
	v_add_f32_e32 v1, v1, v148
	s_waitcnt vmcnt(12)
	v_add_f32_e32 v1, v1, v149
	s_waitcnt vmcnt(11)
	v_add_f32_e32 v1, v1, v150
	s_waitcnt vmcnt(10)
	v_add_f32_e32 v1, v1, v151
	s_waitcnt vmcnt(9)
	v_add_f32_e32 v1, v1, v152
	s_waitcnt vmcnt(8)
	v_add_f32_e32 v1, v1, v153
	s_waitcnt vmcnt(7)
	v_add_f32_e32 v1, v1, v154
	s_waitcnt vmcnt(6)
	v_add_f32_e32 v1, v1, v155
	s_waitcnt vmcnt(5)
	v_add_f32_e32 v1, v1, v156
	s_waitcnt vmcnt(4)
	v_add_f32_e32 v1, v1, v157
	s_waitcnt vmcnt(3)
	v_add_f32_e32 v1, v1, v158
	s_waitcnt vmcnt(2)
	v_add_f32_e32 v1, v1, v159
	s_waitcnt vmcnt(1)
	v_add_f32_e32 v1, v1, v160
	s_waitcnt vmcnt(0)
	v_add_f32_e32 v5, v1, v161
	v_ashrrev_i32_e32 v1, 31, v0
	v_lshl_add_u64 v[6:7], v[0:1], 2, s[6:7]
	v_add_u32_e32 v0, s8, v0
	v_cmp_lt_i32_e32 vcc, s9, v0
	s_or_b64 s[0:1], vcc, s[0:1]
	v_lshl_add_u64 v[2:3], v[2:3], 0, s[10:11]
	global_store_dword v[6:7], v5, off
	s_andn2_b64 exec, exec, s[0:1]
	s_cbranch_execnz .LBB0_88
